# work-queue steal victim: queue q+3 (always another batch, stride coprime with 8 so the 8-visit fallback still covers every queue) instead of q+1
# speedup vs baseline: 1.0047x; 1.0034x over previous
.LBB0_198:
	s_or_b64 exec, exec, s[4:5]
	s_waitcnt lgkmcnt(0)
	s_barrier
	ds_read_b32 v0, v103
	s_movk_i32 s4, 0x1b0
	s_waitcnt lgkmcnt(0)
	v_cmp_gt_i32_e32 vcc, s4, v0
	v_readfirstlane_b32 s6, v0
	s_mov_b64 s[4:5], 0
	s_cbranch_vccnz .LBB0_201
	v_mov_b32_e32 v0, 0x12004
	ds_read_b32 v0, v0
	s_waitcnt lgkmcnt(0)
	v_readfirstlane_b32 s4, v0
	s_cmp_eq_u32 s4, 8
	s_cselect_b32 s4, 0, 6
	s_cmp_gt_i32 s47, s4
	s_mov_b32 s4, 0
	s_cbranch_scc1 .LBB0_202
	s_add_i32 s4, s37, 3
	s_and_b32 s37, s4, 7
	s_add_i32 s47, s47, 1
	s_cbranch_execnz .LBB0_194
	s_branch .LBB0_203

.LBB0_610:
	s_or_b64 exec, exec, s[28:29]
	s_waitcnt lgkmcnt(0)
	s_barrier
	ds_read_b32 v0, v220
	s_movk_i32 s28, 0x120
	s_waitcnt lgkmcnt(0)
	v_cmp_gt_i32_e32 vcc, s28, v0
	v_readfirstlane_b32 s30, v0
	s_mov_b64 s[28:29], 0
	s_cbranch_vccnz .LBB0_613
	v_mov_b32_e32 v0, 0x12004
	ds_read_b32 v0, v0
	s_waitcnt lgkmcnt(0)
	v_readfirstlane_b32 s28, v0
	s_cmp_eq_u32 s28, 8
	s_cselect_b32 s28, 0, 6
	s_cmp_gt_i32 s63, s28
	s_mov_b32 s28, 0
	s_cbranch_scc1 .LBB0_614
	s_add_i32 s28, s52, 3
	s_and_b32 s52, s28, 7
	s_add_i32 s63, s63, 1
	s_cbranch_execnz .LBB0_606
	s_branch .LBB0_615

.LBB0_814:
	s_or_b64 exec, exec, s[2:3]
	s_waitcnt lgkmcnt(0)
	s_barrier
	ds_read_b32 v0, v178
	s_movk_i32 s2, 0x100
	s_waitcnt lgkmcnt(0)
	v_cmp_gt_i32_e32 vcc, s2, v0
	v_readfirstlane_b32 s33, v0
	s_mov_b64 s[2:3], 0
	s_cbranch_vccnz .LBB0_817
	v_readlane_b32 s33, v248, 10
	v_mov_b32_e32 v0, 0x12004
	ds_read_b32 v0, v0
	s_waitcnt lgkmcnt(0)
	v_readfirstlane_b32 s2, v0
	s_cmp_eq_u32 s2, 8
	s_cselect_b32 s2, 0, 6
	s_cmp_gt_i32 s33, s2
	s_mov_b32 s2, 0
	s_cbranch_scc1 .LBB0_818
	v_readlane_b32 s2, v248, 8
	s_add_i32 s2, s2, 3
	s_and_b32 s2, s2, 7
	v_writelane_b32 v248, s2, 8
	s_mov_b64 s[2:3], -1
	s_branch .LBB0_819

.LBB0_896:
	s_or_b64 exec, exec, s[8:9]
	s_waitcnt lgkmcnt(0)
	s_barrier
	ds_read_b32 v0, v105
	s_mov_b64 s[8:9], 0
	s_waitcnt lgkmcnt(0)
	v_cmp_gt_i32_e32 vcc, s15, v0
	v_readfirstlane_b32 s0, v0
	s_cbranch_vccnz .LBB0_899
	v_mov_b32_e32 v0, 0x12004
	ds_read_b32 v0, v0
	s_waitcnt lgkmcnt(0)
	v_readfirstlane_b32 s0, v0
	s_cmp_eq_u32 s0, 8
	s_cselect_b32 s0, 0, 6
	s_cmp_gt_i32 s20, s0
	s_cbranch_scc1 .LBB0_900
	s_add_i32 s0, s14, 3
	s_and_b32 s14, s0, 7
	s_add_i32 s20, s20, 1
	s_cbranch_execnz .LBB0_892
	s_branch .LBB0_901
